# prologue: weight-tile loads issued as one batch (multiplies deferred to next iteration top); row_init loop with next-row prefetch
# speedup vs baseline: 1.0321x; 1.0202x over previous
; #define LAS __attribute__((address_space(3)))
; __device__ __forceinline__ KP kp_fresh(KP k) { asm volatile("" : "+s"(k)); return k; }
; __device__ __forceinline__ int tid_fresh(int wid) { return wid * 64 + lane_id(); }
; __device__ __forceinline__ void prologue_weights(KP kp, LAS float* tile, int wid0) {
;     kp = kp_fresh(kp);
;     const int tid = tid_fresh(wid0);
;     int ti = blockIdx.x;
;     if (ti >= W_TILES) return;
;     WTile w = wtile_decode(kp, ti);
;     float v[8];
;     wtile_load(w, tid, v);
;     int par = 0;
;     for (;;) {
;         LAS float* tb = tile + par * (64 * 65);
.LBB0_81:
	s_or_b64 exec, exec, s[4:5]
	s_waitcnt lgkmcnt(0)
	s_add_u32 s28, s14, 0x5140000
	s_addc_u32 s29, s15, 0
	s_add_u32 s30, s14, 0x4d40000
	s_addc_u32 s31, s15, 0
	s_add_u32 s34, s14, 0x4b40000
	s_addc_u32 s35, s15, 0
	s_add_u32 s36, s14, 0x4900000
	s_addc_u32 s37, s15, 0
	s_add_u32 s40, s14, 0x4600000
	s_addc_u32 s41, s15, 0
	s_add_u32 s42, s14, 0x3000000
	v_lshlrev_b32_e32 v10, 3, v14
	s_addc_u32 s43, s15, 0
	v_and_b32_e32 v10, 56, v10
	s_add_u32 s44, s14, 0x400000
	s_movk_i32 s2, 0x104
	v_ashrrev_i32_e32 v13, 3, v15
	v_mov_b32_e32 v11, 0
	s_addc_u32 s45, s15, 0
	v_and_or_b32 v12, v14, 31, 64
	v_mul_lo_u32 v22, v21, s2
	v_mul_u32_u24_e32 v23, 0x104, v10
	s_mov_b32 s15, 0
	v_lshlrev_b32_e32 v24, 2, v20
	s_movk_i32 s46, 0x3ff
	s_movk_i32 s47, 0x60
	v_lshlrev_b32_e32 v14, 1, v10
	s_mov_b32 s48, 0
	s_mov_b32 s49, s33
	v_mov_b32_e32 v40, 1.0
	v_mov_b32_e32 v41, 1.0
	v_mov_b32_e32 v42, 1.0
	v_mov_b32_e32 v43, 1.0
	v_mov_b32_e32 v44, 1.0
	v_mov_b32_e32 v45, 1.0
	v_mov_b32_e32 v46, 1.0
	v_mov_b32_e32 v47, 1.0
	v_mov_b32_e32 v48, 1.0
	s_branch .LBB0_83

; #define LAS __attribute__((address_space(3)))
; __device__ __forceinline__ void wtile_load(const WTile& w, int tid, float (&v)[8]) {
;     ...
;     const float s = w.scale ? w.scale[n] : 1.0f;
; #pragma unroll
;     for (int i = 0; i < 8; ++i) { const int k = i * 8 + (tid >> 6); v[i] = sc >= 0 ? __builtin_nontemporal_load(w.src + (size_t)(w.k0 + k) * w.Nsrc + sc) * s * (w.kscale ? w.kscale[w.k0 + k] : 1.0f) : 0.f; }
; __device__ __forceinline__ void prologue_weights(KP kp, LAS float* tile, int wid0) {
;     ...
;     for (;;) {
;         LAS float* tb = tile + par * (64 * 65);
; #pragma unroll
;         for (int i = 0; i < 8; ++i) tb[(i * 8 + (tid >> 6)) * 65 + (tid & 63)] = v[i];
;         __syncthreads();
.LBB0_83:
	s_mul_i32 s2, s48, 0x4100
	s_add_i32 s13, s2, 0
	s_add_i32 s50, s49, s38
	s_cmpk_lt_i32 s50, 0x2720
	s_cselect_b64 s[18:19], -1, 0
	s_cmpk_gt_i32 s50, 0x271f
	s_cselect_b64 s[16:17], -1, 0
	s_waitcnt vmcnt(0)
	v_mul_f32_e32 v2, v40, v2
	v_mul_f32_e32 v9, v40, v9
	v_mul_f32_e32 v4, v40, v4
	v_mul_f32_e32 v3, v40, v3
	v_mul_f32_e32 v6, v40, v6
	v_mul_f32_e32 v5, v40, v5
	v_mul_f32_e32 v8, v40, v8
	v_mul_f32_e32 v7, v40, v7
	v_mul_f32_e32 v2, v2, v41
	v_mul_f32_e32 v9, v9, v42
	v_mul_f32_e32 v4, v4, v43
	v_mul_f32_e32 v3, v3, v44
	v_mul_f32_e32 v6, v6, v45
	v_mul_f32_e32 v5, v5, v46
	v_mul_f32_e32 v8, v8, v47
	v_mul_f32_e32 v7, v7, v48
	v_add3_u32 v10, s13, v24, v22
	s_and_b64 vcc, exec, s[16:17]
	s_mov_b64 s[20:21], s[10:11]
	s_mov_b32 s14, s0
	s_mov_b32 s53, s12
	s_mov_b32 s52, s1
	ds_write_b32 v10, v2
	ds_write_b32 v10, v9 offset:2080
	ds_write_b32 v10, v4 offset:4160
	ds_write_b32 v10, v3 offset:6240
	ds_write_b32 v10, v6 offset:8320
	ds_write_b32 v10, v5 offset:10400
	ds_write_b32 v10, v8 offset:12480
	ds_write_b32 v10, v7 offset:14560
	s_waitcnt lgkmcnt(0)
	s_barrier
	s_cbranch_vccnz .LBB0_157
	s_cmpk_gt_i32 s50, 0x15ff
	s_cselect_b64 s[4:5], -1, 0
	s_mov_b64 s[26:27], -1
	s_and_b64 vcc, exec, s[4:5]
	s_cbranch_vccz .LBB0_106
	s_cmpk_gt_u32 s50, 0x20ff
	s_cbranch_scc0 .LBB0_102
	s_cmpk_gt_u32 s50, 0x227f
	s_cbranch_scc0 .LBB0_99
	s_cmpk_gt_u32 s50, 0x239f
	s_cbranch_scc0 .LBB0_96
	s_cmpk_gt_u32 s50, 0x249f
	s_cbranch_scc0 .LBB0_93
	s_cmpk_gt_u32 s50, 0x269f
	s_cbranch_scc0 .LBB0_91
	s_load_dwordx4 s[20:23], s[8:9], 0x60
	s_load_dwordx2 s[26:27], s[8:9], 0x10
	s_add_i32 s51, s50, 0xffffd960
	s_lshr_b32 s14, s51, 4
	s_and_b32 s52, s50, 15
	s_lshl_b64 s[2:3], s[14:15], 18
	s_waitcnt lgkmcnt(0)
	s_add_u32 s2, s20, s2
	s_addc_u32 s3, s21, s3
	s_lshl_b64 s[20:21], s[14:15], 17
	s_add_u32 s20, s28, s20
	s_addc_u32 s21, s29, s21
	s_lshl_b32 s14, s14, 8
	s_lshl_b64 s[24:25], s[14:15], 2
	s_add_u32 s24, s22, s24
	s_addc_u32 s25, s23, s25
	s_lshl_b32 s14, s51, 5
	s_and_b32 s14, s14, 0x7ffff800
	s_lshl_b64 s[22:23], s[14:15], 2
	s_add_u32 s14, s26, s22
	s_addc_u32 s22, s27, s23
	s_lshl_b32 s23, s51, 6
	s_and_b32 s23, s23, 0xc00
	s_add_u32 s14, s14, s23
	s_addc_u32 s23, s22, 0
	s_add_u32 s22, s14, 0x1000
	s_addc_u32 s23, s23, 0
	s_mov_b64 s[26:27], 0

; __device__ __forceinline__ unsigned pk2(float lo, float hi) { const pk_f32x2 v = {lo, hi}; const pk_bf16x2 b = __builtin_convertvector(v, pk_bf16x2); return __builtin_bit_cast(unsigned, b); }
; __device__ __forceinline__ void wtile_load(const WTile& w, int tid, float (&v)[8]) {
;     const int n = w.n0 + (tid & 63);
;     int sc;
;     if (w.map == 1) sc = n < 1024 ? (n >> 6) * 96 + (n & 63) : ((n - 1024) >> 5) * 96 + 64 + ((n - 1024) & 31);
;     else if (w.map == 2) sc = ((n >> 7) & 1) * 2816 + (n >> 8) * 128 + (n & 127);
;     else sc = n < w.Nsrc ? n : -1;
;     const float s = w.scale ? w.scale[n] : 1.0f;
; #pragma unroll
;     for (int i = 0; i < 8; ++i) { const int k = i * 8 + (tid >> 6); v[i] = sc >= 0 ? __builtin_nontemporal_load(w.src + (size_t)(w.k0 + k) * w.Nsrc + sc) * s * (w.kscale ? w.kscale[w.k0 + k] : 1.0f) : 0.f; }
; }
; __device__ __forceinline__ void prologue_weights(KP kp, LAS float* tile, int wid0) {
;     ...
;         WTile wn = w;
;         if (more) { wn = wtile_decode(kp, tn); wtile_load(wn, tid, v); }
;         {
;             const int nl = tid >> 3, kc = tid & 7;
;             float o[8];
; #pragma unroll
;             for (int j = 0; j < 8; ++j) o[j] = tb[(kc * 8 + j) * 65 + nl];
;             u32x4 pk; pk.x = pk2(o[0], o[1]); pk.y = pk2(o[2], o[3]); pk.z = pk2(o[4], o[5]); pk.w = pk2(o[6], o[7]);
;             *(u32x4*)(w.dst + (size_t)(w.n0 + nl) * w.K + w.k0 + kc * 8) = pk;
;         }
.LBB0_121:
	s_cmp_eq_u64 s[24:25], 0
	s_cbranch_scc1 .LBB0_123
	v_ashrrev_i32_e32 v3, 31, v2
	v_lshl_add_u64 v[2:3], v[2:3], 2, s[24:25]
	global_load_dword v40, v[2:3], off
	s_branch .LBB0_124
.LBB0_123:
	v_mov_b32_e32 v40, 1.0
.LBB0_124:
	s_sext_i32_i16 s53, s53
	s_lshl_b32 s53, s53, 6
	v_add_u32_e32 v16, s53, v21
	v_lshl_add_u64 v[18:19], v[10:11], 2, s[2:3]
	v_mul_lo_u32 v26, v16, s51
	v_mov_b32_e32 v27, 0
	v_ashrrev_i32_e32 v17, 31, v16
	s_lshl_b32 s4, s51, 3
	v_mov_b32_e32 v2, 0
	v_mov_b32_e32 v9, 0
	v_mov_b32_e32 v4, 0
	v_mov_b32_e32 v3, 0
	v_mov_b32_e32 v6, 0
	v_mov_b32_e32 v5, 0
	v_mov_b32_e32 v8, 0
	v_mov_b32_e32 v7, 0
	v_mov_b32_e32 v41, 1.0
	v_mov_b32_e32 v42, 1.0
	v_mov_b32_e32 v43, 1.0
	v_mov_b32_e32 v44, 1.0
	v_mov_b32_e32 v45, 1.0
	v_mov_b32_e32 v46, 1.0
	v_mov_b32_e32 v47, 1.0
	v_mov_b32_e32 v48, 1.0
	v_cmp_le_i32_e32 vcc, 0, v10
	s_and_saveexec_b64 s[24:25], vcc
	s_cbranch_execz .Lpw_skipw
	v_lshl_add_u64 v[28:29], v[26:27], 2, v[18:19]
	global_load_dword v2, v[28:29], off nt
	v_add_u32_e32 v26, s4, v26
	v_lshl_add_u64 v[28:29], v[26:27], 2, v[18:19]
	global_load_dword v9, v[28:29], off nt
	v_add_u32_e32 v26, s4, v26
	v_lshl_add_u64 v[28:29], v[26:27], 2, v[18:19]
	global_load_dword v4, v[28:29], off nt
	v_add_u32_e32 v26, s4, v26
	v_lshl_add_u64 v[28:29], v[26:27], 2, v[18:19]
	global_load_dword v3, v[28:29], off nt
	v_add_u32_e32 v26, s4, v26
	v_lshl_add_u64 v[28:29], v[26:27], 2, v[18:19]
	global_load_dword v6, v[28:29], off nt
	v_add_u32_e32 v26, s4, v26
	v_lshl_add_u64 v[28:29], v[26:27], 2, v[18:19]
	global_load_dword v5, v[28:29], off nt
	v_add_u32_e32 v26, s4, v26
	v_lshl_add_u64 v[28:29], v[26:27], 2, v[18:19]
	global_load_dword v8, v[28:29], off nt
	v_add_u32_e32 v26, s4, v26
	v_lshl_add_u64 v[28:29], v[26:27], 2, v[18:19]
	global_load_dword v7, v[28:29], off nt
.Lpw_skipw:
	s_or_b64 exec, exec, s[24:25]
	s_cmp_eq_u64 s[22:23], 0
	s_cbranch_scc1 .Lpw_noks
	v_lshl_add_u64 v[28:29], v[16:17], 2, s[22:23]
	global_load_dword v41, v[28:29], off
	global_load_dword v42, v[28:29], off offset:32
	global_load_dword v43, v[28:29], off offset:64
	global_load_dword v44, v[28:29], off offset:96
	global_load_dword v45, v[28:29], off offset:128
	global_load_dword v46, v[28:29], off offset:160
	global_load_dword v47, v[28:29], off offset:192
	global_load_dword v48, v[28:29], off offset:224
.Lpw_noks:
.LBB0_157:
	v_lshlrev_b32_e32 v10, 2, v13
	v_add3_u32 v10, s13, v10, v23
	ds_read2_b32 v[16:17], v10 offset1:65
	ds_read2_b32 v[18:19], v10 offset0:130 offset1:195
	v_add_u32_e32 v10, 0x400, v10
	ds_read2_b32 v[26:27], v10 offset0:4 offset1:69
	ds_read2_b32 v[28:29], v10 offset0:134 offset1:199
	v_add_u32_e32 v10, s1, v13
	s_waitcnt lgkmcnt(3)
	v_cvt_pk_bf16_f32 v16, v16, v17
	s_waitcnt lgkmcnt(2)
	v_cvt_pk_bf16_f32 v17, v18, v19
	s_waitcnt lgkmcnt(1)
	v_cvt_pk_bf16_f32 v18, v26, v27
	v_mad_u64_u32 v[26:27], s[2:3], s0, v10, 0
	v_ashrrev_i32_e32 v15, 31, v10
	v_mov_b32_e32 v10, v27
	s_waitcnt lgkmcnt(0)
	v_cvt_pk_bf16_f32 v19, v28, v29
	v_mad_u64_u32 v[28:29], s[2:3], s0, v15, v[10:11]
	v_mov_b32_e32 v27, v28
	v_lshl_add_u64 v[26:27], v[26:27], 1, s[10:11]
	s_ashr_i32 s13, s12, 31
	v_lshl_add_u64 v[26:27], s[12:13], 1, v[26:27]
	v_mov_b32_e32 v15, v11
	v_lshl_add_u64 v[26:27], v[26:27], 0, v[14:15]
	s_andn2_b64 vcc, exec, s[18:19]
	global_store_dwordx4 v[26:27], v[16:19], off
	s_cbranch_vccnz .LBB0_82
	s_xor_b32 s48, s48, 1
	s_mov_b32 s1, s52
	s_mov_b32 s12, s53
	s_mov_b32 s0, s14
	s_mov_b64 s[10:11], s[20:21]
	s_mov_b32 s49, s50
	s_branch .LBB0_82

; __device__ __forceinline__ KP kp_fresh(KP k) { asm volatile("" : "+s"(k)); return k; }
; __device__ __forceinline__ int tid_fresh(int wid) { return wid * 64 + lane_id(); }
; __device__ __forceinline__ unsigned pk2(float lo, float hi) { const pk_f32x2 v = {lo, hi}; const pk_bf16x2 b = __builtin_convertvector(v, pk_bf16x2); return __builtin_bit_cast(unsigned, b); }
; __device__ __forceinline__ bf16* hrow16(unsigned char* ws, int r) { return (bf16*)(ws + WS_H16) + ((size_t)r << 10); }
; __device__ __forceinline__ void row_init(KP kp, int wid0) {
;     kp = kp_fresh(kp); const int tid = tid_fresh(wid0); const int lane = tid & 63, wid = tid >> 6;
;     unsigned char* ws = kp->ws; const float* xin = kp->in[0]; const float* meta = kp->in[1]; float* rsd = (float*)(ws + WS_RSTD);
;     for (int row = blockIdx.x * 8 + wid; row < RR; row += gridDim.x * 8) {
;         const int b = row / LL, t = row - b * LL;
;         const float* src = t < NMETA ? meta + (size_t)t * DM : xin + ((size_t)b * SEQ + (t - NMETA)) * DM;
;         bf16* hp = hrow16(ws, row);
;         float ss = 0.f;
; #pragma unroll
;         for (int c = 0; c < 2; ++c) { const f32x4 v0 = __builtin_nontemporal_load((const f32x4*)(src + c * 512 + lane * 8)), v1 = __builtin_nontemporal_load((const f32x4*)(src + c * 512 + lane * 8 + 4));
;             ss += v0[0] * v0[0] + v0[1] * v0[1] + v0[2] * v0[2] + v0[3] * v0[3] + v1[0] * v1[0] + v1[1] * v1[1] + v1[2] * v1[2] + v1[3] * v1[3];
;             u32x4 hw; hw.x = pk2(v0[0], v0[1]); hw.y = pk2(v0[2], v0[3]); hw.z = pk2(v1[0], v1[1]); hw.w = pk2(v1[2], v1[3]);
;             *(u32x4*)(hp + c * 512 + lane * 8) = hw; }
;         ss = wave_sum(ss, lane);
;         if (lane == 0) rsd[row] = 1.0f / sqrtf(ss * (1.0f / DM) + NORM_EPS);
;     }
.LBB0_164:
	s_or_b64 exec, exec, s[2:3]
	s_mov_b64 s[2:3], s[88:89]
	v_mbcnt_lo_u32_b32 v3, -1, 0
	v_mbcnt_hi_u32_b32 v3, -1, v3
	s_mov_b32 s0, 0x8100
	v_add_u32_e32 v2, s61, v3
	v_ashrrev_i32_e32 v2, 6, v2
	v_lshl_add_u32 v2, s33, 3, v2
	v_cmp_gt_i32_e32 vcc, s0, v2
	s_and_saveexec_b64 s[12:13], vcc
	s_cbranch_execz .LBB0_173
	s_load_dwordx2 s[0:1], s[2:3], 0x98
	s_load_dwordx4 s[8:11], s[2:3], 0x0
	v_and_b32_e32 v3, 63, v3
	v_mov_b32_e32 v5, 0
	v_lshlrev_b32_e32 v4, 4, v3
	s_waitcnt lgkmcnt(0)
	s_add_u32 s14, s0, 0x180000
	v_lshlrev_b32_e32 v8, 3, v3
	s_addc_u32 s15, s1, 0
	v_lshl_add_u64 v[6:7], s[0:1], 0, v[4:5]
	s_mov_b64 s[0:1], 0x18f74000
	v_lshlrev_b32_e32 v4, 2, v3
	v_lshl_add_u64 v[6:7], v[6:7], 0, s[0:1]
	v_xor_b32_e32 v16, 0x80, v4
	v_xor_b32_e32 v17, 64, v4
	v_xor_b32_e32 v18, 32, v4
	v_xor_b32_e32 v19, 16, v4
	v_xor_b32_e32 v20, 8, v4
	v_xor_b32_e32 v21, 4, v4
	v_cmp_eq_u32_e64 s[2:3], 0, v3
	s_lshl_b32 s0, s38, 3
	s_mov_b64 s[16:17], 0
	s_mov_b32 s1, 0xfe03f81
	s_movk_i32 s20, 0xf7f0
	v_lshlrev_b32_e32 v8, 2, v8
	v_mov_b32_e32 v9, v5
	v_mov_b32_e32 v22, 0x358637bd
	s_mov_b32 s21, 0xf800000
	v_mov_b32_e32 v23, 0x260
	s_mov_b32 s22, 0x80ff
	s_waitcnt lgkmcnt(0)
	v_mul_hi_i32 v3, v2, s1
	v_lshrrev_b32_e32 v4, 31, v3
	v_ashrrev_i32_e32 v3, 7, v3
	v_add_u32_e32 v10, v3, v4
	v_mad_i32_i24 v12, v10, s20, v2
	v_cmp_lt_i32_e32 vcc, 15, v12
	v_ashrrev_i32_e32 v11, 31, v10
	v_lshlrev_b64 v[10:11], 23, v[10:11]
	v_lshl_add_u64 v[10:11], s[8:9], 0, v[10:11]
	v_add_u32_e32 v3, -16, v12
	v_mov_b32_e32 v4, s10
	v_cndmask_b32_e32 v10, v4, v10, vcc
	v_mov_b32_e32 v4, s11
	v_cndmask_b32_e32 v11, v4, v11, vcc
	v_cndmask_b32_e32 v12, v12, v3, vcc
	v_mov_b32_e32 v13, 0
	v_lshlrev_b64 v[12:13], 12, v[12:13]
	v_lshl_add_u64 v[12:13], v[10:11], 0, v[12:13]
	v_lshl_add_u64 v[14:15], v[12:13], 0, v[8:9]
	global_load_dwordx4 v[40:43], v[14:15], off nt
	global_load_dwordx4 v[44:47], v[14:15], off offset:16 nt
	global_load_dwordx4 v[48:51], v[14:15], off offset:2048 nt
	global_load_dwordx4 v[52:55], v[14:15], off offset:2064 nt
.Lri_loop:
	v_add_u32_e32 v38, s0, v2
	v_cmp_ge_i32_e32 vcc, s22, v38
	s_and_saveexec_b64 s[56:57], vcc
	s_cbranch_execz .Lri_noaddr
	v_mul_hi_i32 v3, v38, s1
	v_lshrrev_b32_e32 v4, 31, v3
	v_ashrrev_i32_e32 v3, 7, v3
	v_add_u32_e32 v10, v3, v4
	v_mad_i32_i24 v12, v10, s20, v38
	v_cmp_lt_i32_e32 vcc, 15, v12
	v_ashrrev_i32_e32 v11, 31, v10
	v_lshlrev_b64 v[10:11], 23, v[10:11]
	v_lshl_add_u64 v[10:11], s[8:9], 0, v[10:11]
	v_add_u32_e32 v3, -16, v12
	v_mov_b32_e32 v4, s10
	v_cndmask_b32_e32 v10, v4, v10, vcc
	v_mov_b32_e32 v4, s11
	v_cndmask_b32_e32 v11, v4, v11, vcc
	v_cndmask_b32_e32 v12, v12, v3, vcc
	v_mov_b32_e32 v13, 0
	v_lshlrev_b64 v[12:13], 12, v[12:13]
	v_lshl_add_u64 v[12:13], v[10:11], 0, v[12:13]
	v_lshl_add_u64 v[58:59], v[12:13], 0, v[8:9]
.Lri_noaddr:
	s_mov_b64 s[58:59], exec
	s_or_b64 exec, exec, s[56:57]
	v_ashrrev_i32_e32 v3, 31, v2
	v_lshlrev_b64 v[28:29], 11, v[2:3]
	v_lshl_add_u64 v[36:37], v[6:7], 0, v[28:29]
	s_waitcnt vmcnt(0)
	v_cvt_pk_bf16_f32 v28, v40, v41
	v_cvt_pk_bf16_f32 v29, v42, v43
	v_cvt_pk_bf16_f32 v30, v44, v45
	v_cvt_pk_bf16_f32 v31, v46, v47
	global_store_dwordx4 v[36:37], v[28:31], off
	v_mul_f32_e32 v4, v41, v41
	v_fmac_f32_e32 v4, v40, v40
	v_fmac_f32_e32 v4, v42, v42
	v_fmac_f32_e32 v4, v43, v43
	v_fmac_f32_e32 v4, v44, v44
	v_fmac_f32_e32 v4, v45, v45
	v_fmac_f32_e32 v4, v46, v46
	v_fmac_f32_e32 v4, v47, v47
	v_mul_f32_e32 v10, v49, v49
	v_fmac_f32_e32 v10, v48, v48
	v_fmac_f32_e32 v10, v50, v50
	v_fmac_f32_e32 v10, v51, v51
	v_fmac_f32_e32 v10, v52, v52
	v_fmac_f32_e32 v10, v53, v53
	v_fmac_f32_e32 v10, v54, v54
	v_fmac_f32_e32 v10, v55, v55
	v_add_f32_e32 v4, v4, v10
	ds_bpermute_b32 v10, v16, v4
	v_cvt_pk_bf16_f32 v12, v48, v49
	v_cvt_pk_bf16_f32 v13, v50, v51
	v_cvt_pk_bf16_f32 v14, v52, v53
	v_cvt_pk_bf16_f32 v15, v54, v55
	global_store_dwordx4 v[36:37], v[12:15], off offset:1024
	s_mov_b64 exec, s[58:59]
	s_cbranch_execz .Lri_noload
	global_load_dwordx4 v[40:43], v[58:59], off nt
	global_load_dwordx4 v[44:47], v[58:59], off offset:16 nt
	global_load_dwordx4 v[48:51], v[58:59], off offset:2048 nt
	global_load_dwordx4 v[52:55], v[58:59], off offset:2064 nt
.Lri_noload:
	s_or_b64 exec, exec, s[56:57]
	s_waitcnt lgkmcnt(0)
	v_add_f32_e32 v4, v4, v10
	ds_bpermute_b32 v10, v17, v4
	s_waitcnt lgkmcnt(0)
	v_add_f32_e32 v4, v4, v10
	ds_bpermute_b32 v10, v18, v4
	s_waitcnt lgkmcnt(0)
	v_add_f32_e32 v4, v4, v10
	ds_bpermute_b32 v10, v19, v4
	s_waitcnt lgkmcnt(0)
	v_add_f32_e32 v4, v4, v10
	ds_bpermute_b32 v10, v20, v4
	s_waitcnt lgkmcnt(0)
	v_add_f32_e32 v4, v4, v10
	ds_bpermute_b32 v10, v21, v4
	s_and_saveexec_b64 s[18:19], s[2:3]
	s_cbranch_execz .Lri_latch
	s_waitcnt lgkmcnt(0)
	v_add_f32_e32 v4, v4, v10
	v_fmamk_f32 v4, v4, 0x3a800000, v22
	v_mul_f32_e32 v10, 0x4f800000, v4
	v_cmp_gt_f32_e32 vcc, s21, v4
	s_nop 1
	v_cndmask_b32_e32 v4, v4, v10, vcc
	v_sqrt_f32_e32 v10, v4
	s_nop 0
	v_add_u32_e32 v11, -1, v10
	v_fma_f32 v13, -v11, v10, v4
	v_add_u32_e32 v12, 1, v10
	v_cmp_ge_f32_e64 s[4:5], 0, v13
	s_nop 1
	v_cndmask_b32_e64 v11, v10, v11, s[4:5]
	v_fma_f32 v10, -v12, v10, v4
	v_cmp_lt_f32_e64 s[4:5], 0, v10
	s_nop 1
	v_cndmask_b32_e64 v10, v11, v12, s[4:5]
	v_mul_f32_e32 v11, 0x37800000, v10
	v_cndmask_b32_e32 v10, v10, v11, vcc
	v_cmp_class_f32_e32 vcc, v4, v23
	s_nop 1
	v_cndmask_b32_e32 v4, v10, v4, vcc
	v_div_scale_f32 v10, s[4:5], v4, v4, 1.0
	v_rcp_f32_e32 v11, v10
	s_nop 0
	v_fma_f32 v12, -v10, v11, 1.0
	v_fmac_f32_e32 v11, v12, v11
	v_div_scale_f32 v12, vcc, 1.0, v4, 1.0
	v_mul_f32_e32 v13, v12, v11
	v_fma_f32 v14, -v10, v13, v12
	v_fmac_f32_e32 v13, v14, v11
	v_fma_f32 v10, -v10, v13, v12
	v_div_fmas_f32 v10, v10, v11, v13
	v_div_fixup_f32 v4, v10, v4, 1.0
	v_lshl_add_u64 v[10:11], v[2:3], 2, s[14:15]
	global_store_dword v[10:11], v4, off
.Lri_latch:
	s_or_b64 exec, exec, s[18:19]
	s_waitcnt lgkmcnt(0)
	v_mov_b32_e32 v2, v38
	s_mov_b64 exec, s[58:59]
	s_cbranch_execnz .Lri_loop
